# gates-phase load balance: FNet stage-2 items (one per wave) all run on first-launched blocks (waves 0-1023 take items gw and gw+1024)
# speedup vs baseline: 1.0186x; 1.0016x over previous
.LBB0_742:
	s_cmp_gt_i32 s52, 4
	s_cselect_b64 s[0:1], -1, 0
	s_cmp_lt_i32 s53, 5
	s_cselect_b64 s[2:3], -1, 0
	s_or_b64 s[0:1], s[0:1], s[2:3]
	s_and_b64 vcc, exec, s[0:1]
	v_lshrrev_b32_e32 v186, 6, v1
	v_lshrrev_b32_e32 v187, 2, v1
	s_cbranch_vccnz .LBB0_825
	v_readlane_b32 s0, v248, 0
	v_and_b32_e32 v2, 8, v187
	v_mov_b32_e32 v37, 0
	v_lshl_add_u32 v58, s0, 2, v186
	s_movk_i32 s0, 0x400
	v_cmp_gt_i32_e32 vcc, s0, v58
	v_lshlrev_b32_e32 v34, 1, v2
	s_and_saveexec_b64 s[0:1], vcc
	s_cbranch_execz .LBB0_746
	v_mov_b32_e32 v2, 0x1000
	v_lshlrev_b32_e32 v36, 8, v132
	v_lshl_or_b32 v59, v132, 6, v2
	v_lshl_add_u64 v[2:3], s[82:83], 0, v[36:37]
	v_mov_b32_e32 v35, v37
	v_lshl_add_u64 v[2:3], v[2:3], 0, v[34:35]
	s_mov_b64 s[4:5], 0xe908000
	v_lshl_add_u64 v[38:39], v[2:3], 0, s[4:5]
	s_mov_b64 s[4:5], 0xe90a000
	v_lshl_add_u64 v[40:41], v[2:3], 0, s[4:5]
	s_mov_b64 s[4:5], 0xe90a020
	v_lshl_add_u64 v[42:43], v[2:3], 0, s[4:5]
	s_mov_b64 s[4:5], 0xe90a040
	v_lshl_add_u64 v[44:45], v[2:3], 0, s[4:5]
	s_mov_b64 s[4:5], 0xe90a060
	v_lshl_add_u64 v[46:47], v[2:3], 0, s[4:5]
	s_mov_b64 s[4:5], 0xe90a080
	v_lshl_add_u64 v[48:49], v[2:3], 0, s[4:5]
	s_mov_b64 s[4:5], 0xe90a0a0
	v_lshl_add_u64 v[50:51], v[2:3], 0, s[4:5]
	s_mov_b64 s[4:5], 0xe90a0c0
	v_lshl_add_u64 v[52:53], v[2:3], 0, s[4:5]
	s_mov_b64 s[4:5], 0xe90a0e0
	v_lshl_add_u64 v[54:55], v[2:3], 0, s[4:5]
	v_lshl_add_u64 v[2:3], s[82:83], 0, v[34:35]
	s_mov_b64 s[4:5], 0xc900000
	s_lshl_b32 s7, s50, 1
	v_lshl_add_u64 v[56:57], v[2:3], 0, s[4:5]
	v_lshlrev_b32_e32 v2, 2, v186
	v_readlane_b32 s4, v248, 0
	s_add_u32 s2, s82, 0xd500000
	s_addc_u32 s3, s83, 0
	v_lshl_add_u32 v60, s4, 4, v2
	v_lshlrev_b32_e32 v2, 5, v186
	s_lshl_b32 s8, s50, 3
	v_lshl_add_u32 v61, s4, 7, v2
	s_lshl_b32 s9, s50, 6
	s_mov_b64 s[4:5], 0
	s_mov_b32 s6, 0x3ab504f3
	s_movk_i32 s10, 0x7ff

.LBB0_1634:
	s_cmp_gt_i32 s52, 11
	s_cselect_b64 s[0:1], -1, 0
	s_cmp_lt_i32 s53, 12
	s_cselect_b64 s[2:3], -1, 0
	s_or_b64 s[0:1], s[0:1], s[2:3]
	s_and_b64 vcc, exec, s[0:1]
	s_cbranch_vccnz .LBB0_1717
	v_readlane_b32 s0, v248, 0
	v_and_b32_e32 v2, 8, v187
	v_mov_b32_e32 v37, 0
	v_lshl_add_u32 v58, s0, 2, v186
	s_movk_i32 s0, 0x400
	v_cmp_gt_i32_e32 vcc, s0, v58
	v_lshlrev_b32_e32 v34, 1, v2
	s_and_saveexec_b64 s[0:1], vcc
	s_cbranch_execz .LBB0_1638
	v_mov_b32_e32 v2, 0x1000
	v_lshlrev_b32_e32 v36, 8, v132
	v_lshl_or_b32 v59, v132, 6, v2
	v_lshl_add_u64 v[2:3], s[82:83], 0, v[36:37]
	v_mov_b32_e32 v35, v37
	v_lshl_add_u64 v[2:3], v[2:3], 0, v[34:35]
	s_mov_b64 s[4:5], 0xe908000
	v_lshl_add_u64 v[38:39], v[2:3], 0, s[4:5]
	s_mov_b64 s[4:5], 0xe90a000
	v_lshl_add_u64 v[40:41], v[2:3], 0, s[4:5]
	s_mov_b64 s[4:5], 0xe90a020
	v_lshl_add_u64 v[42:43], v[2:3], 0, s[4:5]
	s_mov_b64 s[4:5], 0xe90a040
	v_lshl_add_u64 v[44:45], v[2:3], 0, s[4:5]
	s_mov_b64 s[4:5], 0xe90a060
	v_lshl_add_u64 v[46:47], v[2:3], 0, s[4:5]
	s_mov_b64 s[4:5], 0xe90a080
	v_lshl_add_u64 v[48:49], v[2:3], 0, s[4:5]
	s_mov_b64 s[4:5], 0xe90a0a0
	v_lshl_add_u64 v[50:51], v[2:3], 0, s[4:5]
	s_mov_b64 s[4:5], 0xe90a0c0
	v_lshl_add_u64 v[52:53], v[2:3], 0, s[4:5]
	s_mov_b64 s[4:5], 0xe90a0e0
	v_lshl_add_u64 v[54:55], v[2:3], 0, s[4:5]
	v_lshl_add_u64 v[2:3], s[82:83], 0, v[34:35]
	s_mov_b64 s[4:5], 0xc900000
	s_lshl_b32 s7, s50, 1
	v_lshl_add_u64 v[56:57], v[2:3], 0, s[4:5]
	v_lshlrev_b32_e32 v2, 2, v186
	v_readlane_b32 s4, v248, 0
	s_add_u32 s2, s82, 0xd500000
	s_addc_u32 s3, s83, 0
	v_lshl_add_u32 v60, s4, 4, v2
	v_lshlrev_b32_e32 v2, 5, v186
	s_lshl_b32 s8, s50, 3
	v_lshl_add_u32 v61, s4, 7, v2
	s_lshl_b32 s9, s50, 6
	s_mov_b64 s[4:5], 0
	s_mov_b32 s6, 0x3ab504f3
	s_movk_i32 s10, 0x7ff
